# plus grid barrier leaders no longer add the (now unread) per-XCD generation word before their acquire
# baseline (speedup 1.0000x reference)
.LBB0_200:
	s_or_b64 exec, exec, s[18:19]
	s_xor_b64 s[10:11], s[20:21], -1
	s_and_saveexec_b64 s[18:19], s[10:11]
	s_xor_b64 s[18:19], exec, s[18:19]
	s_cbranch_execz .LBB0_203
	s_mov_b64 s[10:11], exec
	v_mbcnt_lo_u32_b32 v1, s10, 0
	v_mbcnt_hi_u32_b32 v1, s11, v1
	v_cmp_eq_u32_e32 vcc, 0, v1
	s_and_b64 s[18:19], exec, vcc
	s_mov_b64 exec, s[18:19]
	s_cbranch_execz .LBB0_203
	s_bcnt1_i32_b64 s10, s[10:11]
	v_mov_b32_e32 v1, 0
	v_mov_b32_e32 v2, s10
	global_atomic_add v1, v2, s[14:15]
.LBB0_203:
	s_or_b64 exec, exec, s[12:13]
	s_waitcnt vmcnt(0)
	buffer_inv sc1
	s_waitcnt vmcnt(0)
.LBB0_204:
	s_or_b64 exec, exec, s[6:7]
	s_waitcnt lgkmcnt(0)
	s_barrier

.LBB0_372:
	s_or_b64 exec, exec, s[18:19]
	s_xor_b64 s[10:11], s[20:21], -1
	s_and_saveexec_b64 s[18:19], s[10:11]
	s_xor_b64 s[18:19], exec, s[18:19]
	s_cbranch_execz .LBB0_375
	s_mov_b64 s[10:11], exec
	v_mbcnt_lo_u32_b32 v1, s10, 0
	v_mbcnt_hi_u32_b32 v1, s11, v1
	v_cmp_eq_u32_e32 vcc, 0, v1
	s_and_b64 s[18:19], exec, vcc
	s_mov_b64 exec, s[18:19]
	s_cbranch_execz .LBB0_375
	s_bcnt1_i32_b64 s10, s[10:11]
	v_mov_b32_e32 v1, 0
	v_mov_b32_e32 v2, s10
	global_atomic_add v1, v2, s[14:15]
.LBB0_375:
	s_or_b64 exec, exec, s[12:13]
	s_waitcnt vmcnt(0)
	buffer_inv sc1
	s_waitcnt vmcnt(0)
.LBB0_376:
	s_or_b64 exec, exec, s[6:7]
	s_waitcnt lgkmcnt(0)
	s_barrier

.LBB0_451:
	s_or_b64 exec, exec, s[18:19]
	s_xor_b64 s[10:11], s[20:21], -1
	s_and_saveexec_b64 s[18:19], s[10:11]
	s_xor_b64 s[18:19], exec, s[18:19]
	s_cbranch_execz .LBB0_454
	s_mov_b64 s[10:11], exec
	v_mbcnt_lo_u32_b32 v1, s10, 0
	v_mbcnt_hi_u32_b32 v1, s11, v1
	v_cmp_eq_u32_e32 vcc, 0, v1
	s_and_b64 s[18:19], exec, vcc
	s_mov_b64 exec, s[18:19]
	s_cbranch_execz .LBB0_454
	s_bcnt1_i32_b64 s10, s[10:11]
	v_mov_b32_e32 v1, 0
	v_mov_b32_e32 v2, s10
	global_atomic_add v1, v2, s[14:15]
.LBB0_454:
	s_or_b64 exec, exec, s[12:13]
	s_waitcnt vmcnt(0)
	buffer_inv sc1
	s_waitcnt vmcnt(0)
.LBB0_455:
	s_or_b64 exec, exec, s[6:7]
	s_waitcnt lgkmcnt(0)
	s_barrier

.LBB0_532:
	s_or_b64 exec, exec, s[18:19]
	s_xor_b64 s[10:11], s[20:21], -1
	s_and_saveexec_b64 s[18:19], s[10:11]
	s_xor_b64 s[18:19], exec, s[18:19]
	s_cbranch_execz .LBB0_535
	s_mov_b64 s[10:11], exec
	v_mbcnt_lo_u32_b32 v1, s10, 0
	v_mbcnt_hi_u32_b32 v1, s11, v1
	v_cmp_eq_u32_e32 vcc, 0, v1
	s_and_b64 s[18:19], exec, vcc
	s_mov_b64 exec, s[18:19]
	s_cbranch_execz .LBB0_535
	s_bcnt1_i32_b64 s10, s[10:11]
	v_mov_b32_e32 v1, 0
	v_mov_b32_e32 v2, s10
	global_atomic_add v1, v2, s[14:15]
.LBB0_535:
	s_or_b64 exec, exec, s[12:13]
	s_waitcnt vmcnt(0)
	buffer_inv sc1
	s_waitcnt vmcnt(0)
.LBB0_536:
	s_or_b64 exec, exec, s[6:7]
	s_waitcnt lgkmcnt(0)
	s_barrier

.LBB0_624:
	s_or_b64 exec, exec, s[18:19]
	s_xor_b64 s[10:11], s[20:21], -1
	s_and_saveexec_b64 s[18:19], s[10:11]
	s_xor_b64 s[18:19], exec, s[18:19]
	s_cbranch_execz .LBB0_627
	s_mov_b64 s[10:11], exec
	v_mbcnt_lo_u32_b32 v1, s10, 0
	v_mbcnt_hi_u32_b32 v1, s11, v1
	v_cmp_eq_u32_e32 vcc, 0, v1
	s_and_b64 s[18:19], exec, vcc
	s_mov_b64 exec, s[18:19]
	s_cbranch_execz .LBB0_627
	s_bcnt1_i32_b64 s10, s[10:11]
	v_mov_b32_e32 v1, 0
	v_mov_b32_e32 v2, s10
	global_atomic_add v1, v2, s[14:15]
.LBB0_627:
	s_or_b64 exec, exec, s[12:13]
	s_waitcnt vmcnt(0)
	buffer_inv sc1
	s_waitcnt vmcnt(0)
.LBB0_628:
	s_or_b64 exec, exec, s[6:7]
	s_waitcnt lgkmcnt(0)
	s_barrier

.LBB0_842:
	s_or_b64 exec, exec, s[12:13]
	s_xor_b64 s[6:7], s[14:15], -1
	s_and_saveexec_b64 s[12:13], s[6:7]
	s_xor_b64 s[12:13], exec, s[12:13]
	s_cbranch_execz .LBB0_845
	s_mov_b64 s[6:7], exec
	v_mbcnt_lo_u32_b32 v1, s6, 0
	v_mbcnt_hi_u32_b32 v1, s7, v1
	v_cmp_eq_u32_e32 vcc, 0, v1
	s_and_b64 s[12:13], exec, vcc
	s_mov_b64 exec, s[12:13]
	s_cbranch_execz .LBB0_845
	s_bcnt1_i32_b64 s6, s[6:7]
	v_mov_b32_e32 v1, 0
	v_mov_b32_e32 v2, s6
	global_atomic_add v1, v2, s[10:11]
.LBB0_845:
	s_or_b64 exec, exec, s[8:9]
	s_waitcnt vmcnt(0)
	buffer_inv sc1
	s_waitcnt vmcnt(0)
.LBB0_846:
	s_or_b64 exec, exec, s[0:1]
	s_waitcnt lgkmcnt(0)
	s_barrier

.LBB0_926:
	s_or_b64 exec, exec, s[14:15]
	s_xor_b64 s[8:9], s[16:17], -1
	s_and_saveexec_b64 s[14:15], s[8:9]
	s_xor_b64 s[14:15], exec, s[14:15]
	s_cbranch_execz .LBB0_929
	s_mov_b64 s[8:9], exec
	v_mbcnt_lo_u32_b32 v1, s8, 0
	v_mbcnt_hi_u32_b32 v1, s9, v1
	v_cmp_eq_u32_e32 vcc, 0, v1
	s_and_b64 s[14:15], exec, vcc
	s_mov_b64 exec, s[14:15]
	s_cbranch_execz .LBB0_929
	s_bcnt1_i32_b64 s8, s[8:9]
	v_mov_b32_e32 v1, 0
	v_mov_b32_e32 v2, s8
	global_atomic_add v1, v2, s[12:13]
.LBB0_929:
	s_or_b64 exec, exec, s[10:11]
	s_waitcnt vmcnt(0)
	buffer_inv sc1
	s_waitcnt vmcnt(0)
.LBB0_930:
	s_or_b64 exec, exec, s[4:5]
	s_waitcnt lgkmcnt(0)
	s_barrier

.LBB0_1117:
	s_or_b64 exec, exec, s[14:15]
	s_xor_b64 s[8:9], s[16:17], -1
	s_and_saveexec_b64 s[14:15], s[8:9]
	s_xor_b64 s[14:15], exec, s[14:15]
	s_cbranch_execz .LBB0_1120
	s_mov_b64 s[8:9], exec
	v_mbcnt_lo_u32_b32 v1, s8, 0
	v_mbcnt_hi_u32_b32 v1, s9, v1
	v_cmp_eq_u32_e32 vcc, 0, v1
	s_and_b64 s[14:15], exec, vcc
	s_mov_b64 exec, s[14:15]
	s_cbranch_execz .LBB0_1120
	s_bcnt1_i32_b64 s8, s[8:9]
	v_mov_b32_e32 v1, 0
	v_mov_b32_e32 v2, s8
	global_atomic_add v1, v2, s[12:13]
.LBB0_1120:
	s_or_b64 exec, exec, s[10:11]
	s_waitcnt vmcnt(0)
	buffer_inv sc1
	s_waitcnt vmcnt(0)
.LBB0_1121:
	s_or_b64 exec, exec, s[4:5]
	s_waitcnt lgkmcnt(0)
	s_barrier

.LBB0_1177:
	s_or_b64 exec, exec, s[14:15]
	s_xor_b64 s[8:9], s[16:17], -1
	s_and_saveexec_b64 s[14:15], s[8:9]
	s_xor_b64 s[14:15], exec, s[14:15]
	s_cbranch_execz .LBB0_1180
	s_mov_b64 s[8:9], exec
	v_mbcnt_lo_u32_b32 v1, s8, 0
	v_mbcnt_hi_u32_b32 v1, s9, v1
	v_cmp_eq_u32_e32 vcc, 0, v1
	s_and_b64 s[14:15], exec, vcc
	s_mov_b64 exec, s[14:15]
	s_cbranch_execz .LBB0_1180
	s_bcnt1_i32_b64 s3, s[8:9]
	v_mov_b32_e32 v1, 0
	v_mov_b32_e32 v2, s3
	global_atomic_add v1, v2, s[12:13]
.LBB0_1180:
	s_or_b64 exec, exec, s[10:11]
	s_waitcnt vmcnt(0)
	buffer_inv sc1
	s_waitcnt vmcnt(0)
.LBB0_1181:
	s_or_b64 exec, exec, s[4:5]
	s_waitcnt lgkmcnt(0)
	s_barrier
